# speedup vs baseline: 1.0027x; 1.0027x over previous
; __device__ __forceinline__ float wave_sum(float v) {
;   for (int o = 32; o > 0; o >>= 1) v += __shfl_xor(v, o);
;   return v;
; }
; __device__ void phase_norm(const Params& p, int src_is_input, const bf16_t* delta, const float* gain, int final_out, int dry) {
;     ...
;     ss = wave_sum(ss);
;     const float rr = rsqrtf(ss * (1.f / 1024.f) + 1e-6f);
;     float y[16];
;     float ss2 = 0.f;
; #pragma unroll
;     for (int j = 0; j < 16; ++j) { y[j] = xv[j] + dv[j] * rr * gq[j]; ss2 += y[j] * y[j]; }
;     if (!dry) {
; #pragma unroll
;       for (int i = 0; i < 2; ++i) {
;         if (final_out) {
;           float* op = p.out + (size_t)row * DM + i * 512 + lane * 8;
;           *(float4*)op = make_float4(y[i * 8 + 0], y[i * 8 + 1], y[i * 8 + 2], y[i * 8 + 3]);
;           *(float4*)(op + 4) = make_float4(y[i * 8 + 4], y[i * 8 + 5], y[i * 8 + 6], y[i * 8 + 7]);
;         } else {
;           uint4 o;
;           o.x = pack2(y[i * 8 + 0], y[i * 8 + 1]); o.y = pack2(y[i * 8 + 2], y[i * 8 + 3]);
;           o.z = pack2(y[i * 8 + 4], y[i * 8 + 5]); o.w = pack2(y[i * 8 + 6], y[i * 8 + 7]);
;           *(uint4*)(xb + (size_t)row * DM + i * 512 + lane * 8) = o;
;         }
;       }
.LBB0_1289:
	s_or_b64 exec, exec, s[26:27]
	v_lshlrev_b32_e32 v64, 16, v46
	v_and_b32_e32 v65, 0xffff0000, v46
	v_lshlrev_b32_e32 v46, 16, v47
	v_and_b32_e32 v47, 0xffff0000, v47
	v_lshlrev_b32_e32 v74, 16, v42
	v_and_b32_e32 v75, 0xffff0000, v42
	v_lshlrev_b32_e32 v76, 16, v43
	v_and_b32_e32 v77, 0xffff0000, v43
	v_pk_mul_f32 v[42:43], v[64:65], v[64:65]
	v_lshlrev_b32_e32 v78, 16, v44
	v_and_b32_e32 v79, 0xffff0000, v44
	v_lshlrev_b32_e32 v80, 16, v45
	v_and_b32_e32 v81, 0xffff0000, v45
	v_pk_mul_f32 v[44:45], v[46:47], v[46:47]
	v_add_f32_e32 v0, v42, v43
	v_lshlrev_b32_e32 v72, 16, v48
	v_and_b32_e32 v73, 0xffff0000, v48
	v_add_f32_e32 v0, v0, v44
	v_pk_mul_f32 v[82:83], v[72:73], v[72:73]
	v_add_f32_e32 v0, v45, v0
	v_lshlrev_b32_e32 v48, 16, v49
	v_and_b32_e32 v49, 0xffff0000, v49
	v_add_f32_e32 v0, v82, v0
	v_pk_mul_f32 v[84:85], v[48:49], v[48:49]
	v_add_f32_e32 v0, v83, v0
	v_add_f32_e32 v0, v84, v0
	v_pk_mul_f32 v[86:87], v[74:75], v[74:75]
	v_add_f32_e32 v0, v85, v0
	v_add_f32_e32 v0, v86, v0
	v_pk_mul_f32 v[88:89], v[76:77], v[76:77]
	v_add_f32_e32 v0, v87, v0
	v_add_f32_e32 v0, v88, v0
	v_pk_mul_f32 v[90:91], v[78:79], v[78:79]
	v_add_f32_e32 v0, v89, v0
	v_add_f32_e32 v0, v90, v0
	v_pk_mul_f32 v[92:93], v[80:81], v[80:81]
	v_add_f32_e32 v0, v91, v0
	v_add_f32_e32 v0, v92, v0
	v_add_f32_e32 v0, v93, v0
	v_lshlrev_b32_e32 v82, 16, v34
	v_and_b32_e32 v83, 0xffff0000, v34
	v_lshlrev_b32_e32 v84, 16, v35
	v_and_b32_e32 v85, 0xffff0000, v35
	v_lshlrev_b32_e32 v86, 16, v36
	v_and_b32_e32 v87, 0xffff0000, v36
	v_lshlrev_b32_e32 v88, 16, v37
	v_and_b32_e32 v89, 0xffff0000, v37
	v_lshlrev_b32_e32 v42, 16, v38
	v_lshlrev_b32_e32 v44, 16, v40
	v_and_b32_e32 v43, 0xffff0000, v38
	v_lshlrev_b32_e32 v38, 16, v39
	v_and_b32_e32 v39, 0xffff0000, v39
	v_and_b32_e32 v45, 0xffff0000, v40
	v_lshlrev_b32_e32 v40, 16, v41
	v_and_b32_e32 v41, 0xffff0000, v41
	s_nop 1
	v_add_f32_dpp v0, v0, v0 quad_perm:[1,0,3,2] row_mask:0xf bank_mask:0xf
	s_nop 1
	v_add_f32_dpp v0, v0, v0 quad_perm:[2,3,0,1] row_mask:0xf bank_mask:0xf
	s_nop 1
	v_add_f32_dpp v0, v0, v0 row_ror:4 row_mask:0xf bank_mask:0xf
	s_nop 1
	v_add_f32_dpp v0, v0, v0 row_ror:8 row_mask:0xf bank_mask:0xf
	v_mov_b32_e32 v176, v0
	s_nop 1
	v_permlane16_swap_b32_e32 v0, v176
	s_nop 1
	v_add_f32_e32 v0, v0, v176
	v_mov_b32_e32 v176, v0
	s_nop 1
	v_permlane32_swap_b32_e32 v0, v176
	s_nop 1
	v_add_f32_e32 v0, v0, v176
	v_fmamk_f32 v0, v0, 0x3a800000, v216
	v_mul_f32_e32 v34, 0x4b800000, v0
	v_cmp_gt_f32_e32 vcc, s44, v0
	s_nop 1
	v_cndmask_b32_e32 v0, v0, v34, vcc
	v_rsq_f32_e32 v0, v0
	s_nop 0
	v_mul_f32_e32 v34, 0x45800000, v0
	v_cndmask_b32_e32 v0, v0, v34, vcc
	v_pk_mul_f32 v[34:35], v[0:1], v[64:65] op_sel_hi:[0,1]
	v_pk_mul_f32 v[36:37], v[0:1], v[46:47] op_sel_hi:[0,1]
	v_pk_fma_f32 v[34:35], v[6:7], v[34:35], v[42:43]
	v_pk_fma_f32 v[36:37], v[8:9], v[36:37], v[38:39]
	v_pk_mul_f32 v[38:39], v[0:1], v[72:73] op_sel_hi:[0,1]
	v_pk_mul_f32 v[42:43], v[0:1], v[48:49] op_sel_hi:[0,1]
	v_pk_fma_f32 v[38:39], v[2:3], v[38:39], v[44:45]
	v_pk_fma_f32 v[40:41], v[4:5], v[42:43], v[40:41]
	v_pk_mul_f32 v[42:43], v[0:1], v[74:75] op_sel_hi:[0,1]
	v_pk_mul_f32 v[44:45], v[0:1], v[76:77] op_sel_hi:[0,1]
	v_pk_mul_f32 v[46:47], v[0:1], v[78:79] op_sel_hi:[0,1]
	v_pk_mul_f32 v[48:49], v[0:1], v[80:81] op_sel_hi:[0,1]
	v_pk_fma_f32 v[42:43], v[14:15], v[42:43], v[82:83]
	v_pk_fma_f32 v[44:45], v[16:17], v[44:45], v[84:85]
	v_pk_fma_f32 v[46:47], v[10:11], v[46:47], v[86:87]
	s_andn2_b64 vcc, exec, s[22:23]
	v_pk_fma_f32 v[48:49], v[12:13], v[48:49], v[88:89]
	s_cbranch_vccnz .LBB0_1298
	v_lshl_add_u64 v[64:65], v[54:55], 0, v[52:53]
	s_mov_b64 s[26:27], -1
	s_and_b64 vcc, exec, s[10:11]
	s_cbranch_vccz .LBB0_1294
	v_add_co_u32_e32 v76, vcc, 0x61a6000, v64
	v_cvt_pk_bf16_f32 v72, v34, v35
	v_cvt_pk_bf16_f32 v73, v36, v37
	v_cvt_pk_bf16_f32 v74, v38, v39
	v_cvt_pk_bf16_f32 v75, v40, v41
	v_addc_co_u32_e32 v77, vcc, 0, v65, vcc
	global_store_dwordx4 v[76:77], v[72:75], off
	s_cbranch_execz .LBB0_1295

; __device__ __forceinline__ float wave_sum(float v) {
;   for (int o = 32; o > 0; o >>= 1) v += __shfl_xor(v, o);
;   return v;
; }
; __device__ void phase_norm(const Params& p, int src_is_input, const bf16_t* delta, const float* gain, int final_out, int dry) {
;     ...
;     if (!final_out) {
;       ss2 = wave_sum(ss2);
;       if (lane == 0 && (!dry || ss2 < 0.f)) rstd[row] = rsqrtf(ss2 * (1.f / 1024.f) + 1e-6f);
;     }
.LBB0_1298:
	s_andn2_b64 vcc, exec, s[10:11]
	s_cbranch_vccnz .LBB0_1286
	v_pk_mul_f32 v[34:35], v[34:35], v[34:35]
	v_pk_mul_f32 v[36:37], v[36:37], v[36:37]
	v_add_f32_e32 v0, v34, v35
	v_add_f32_e32 v0, v36, v0
	v_pk_mul_f32 v[38:39], v[38:39], v[38:39]
	v_add_f32_e32 v0, v37, v0
	v_add_f32_e32 v0, v38, v0
	v_pk_mul_f32 v[40:41], v[40:41], v[40:41]
	v_add_f32_e32 v0, v39, v0
	v_add_f32_e32 v0, v40, v0
	v_pk_mul_f32 v[42:43], v[42:43], v[42:43]
	v_add_f32_e32 v0, v41, v0
	v_add_f32_e32 v0, v42, v0
	v_pk_mul_f32 v[44:45], v[44:45], v[44:45]
	v_add_f32_e32 v0, v43, v0
	v_add_f32_e32 v0, v44, v0
	v_pk_mul_f32 v[46:47], v[46:47], v[46:47]
	v_add_f32_e32 v0, v45, v0
	v_add_f32_e32 v0, v46, v0
	v_pk_mul_f32 v[48:49], v[48:49], v[48:49]
	v_add_f32_e32 v0, v47, v0
	v_add_f32_e32 v0, v48, v0
	v_add_f32_e32 v0, v49, v0
	s_nop 1
	v_add_f32_dpp v0, v0, v0 quad_perm:[1,0,3,2] row_mask:0xf bank_mask:0xf
	s_nop 1
	v_add_f32_dpp v0, v0, v0 quad_perm:[2,3,0,1] row_mask:0xf bank_mask:0xf
	s_nop 1
	v_add_f32_dpp v0, v0, v0 row_ror:4 row_mask:0xf bank_mask:0xf
	s_nop 1
	v_add_f32_dpp v0, v0, v0 row_ror:8 row_mask:0xf bank_mask:0xf
	v_mov_b32_e32 v176, v0
	s_nop 1
	v_permlane16_swap_b32_e32 v0, v176
	s_nop 1
	v_add_f32_e32 v0, v0, v176
	v_mov_b32_e32 v176, v0
	s_nop 1
	v_permlane32_swap_b32_e32 v0, v176
	s_nop 1
	v_add_f32_e32 v0, v0, v176
	v_cmp_gt_f32_e32 vcc, 0, v0
	s_or_b64 s[26:27], s[22:23], vcc
	s_and_b64 s[30:31], s[4:5], s[26:27]
	s_and_saveexec_b64 s[26:27], s[30:31]
	s_cbranch_execz .LBB0_1285
	v_fmamk_f32 v0, v0, 0x3a800000, v216
	v_mul_f32_e32 v34, 0x4b800000, v0
	v_cmp_gt_f32_e32 vcc, s44, v0
	s_nop 1
	v_cndmask_b32_e32 v0, v0, v34, vcc
	v_rsq_f32_e32 v0, v0
	s_nop 0
	v_mul_f32_e32 v34, 0x45800000, v0
	v_cndmask_b32_e32 v0, v0, v34, vcc
	global_store_dword v[62:63], v0, off
	s_branch .LBB0_1285
